# FFN1 epilogue: conv-weight staging values fetched before the K loop; conv+SiLU stage rewritten by hand with DPP-fused FMAs (no packed ops, no DPP movs)
# speedup vs baseline: 1.0028x; 1.0028x over previous
.LBB0_69:
	s_ashr_i32 s65, s64, 31
	s_lshl_b64 s[34:35], s[64:65], 19
	s_add_u32 s68, s8, s34
	s_addc_u32 s69, s53, s35
	s_and_b64 s[0:1], s[0:1], exec
	s_cselect_b32 s23, s69, s31
	s_cselect_b32 s28, s68, s30
	s_add_u32 s0, s26, 0x40080
	s_addc_u32 s1, s27, 0
	s_add_u32 s33, s30, 0x100
	v_mov_b32_e32 v2, 0
	s_addc_u32 s34, s31, 0
	s_mov_b32 s35, -2
	v_mov_b32_e32 v3, v2
	v_mov_b32_e32 v4, v2
	v_mov_b32_e32 v5, v2
	v_mov_b32_e32 v66, v2
	v_mov_b32_e32 v67, v2
	v_mov_b32_e32 v68, v2
	v_mov_b32_e32 v69, v2
	v_mov_b32_e32 v10, v2
	v_mov_b32_e32 v11, v2
	v_mov_b32_e32 v12, v2
	v_mov_b32_e32 v13, v2
	v_mov_b32_e32 v74, v2
	v_mov_b32_e32 v75, v2
	v_mov_b32_e32 v76, v2
	v_mov_b32_e32 v77, v2
	v_mov_b32_e32 v18, v2
	v_mov_b32_e32 v19, v2
	v_mov_b32_e32 v20, v2
	v_mov_b32_e32 v21, v2
	v_mov_b32_e32 v82, v2
	v_mov_b32_e32 v83, v2
	v_mov_b32_e32 v84, v2
	v_mov_b32_e32 v85, v2
	v_mov_b32_e32 v26, v2
	s_waitcnt lgkmcnt(0)
	v_mov_b32_e32 v27, v2
	v_mov_b32_e32 v28, v2
	v_mov_b32_e32 v29, v2
	v_mov_b32_e32 v90, v2
	v_mov_b32_e32 v91, v2
	v_mov_b32_e32 v92, v2
	v_mov_b32_e32 v93, v2
	v_mov_b32_e32 v6, v2
	v_mov_b32_e32 v7, v2
	v_mov_b32_e32 v8, v2
	v_mov_b32_e32 v9, v2
	v_mov_b32_e32 v70, v2
	v_mov_b32_e32 v71, v2
	v_mov_b32_e32 v72, v2
	v_mov_b32_e32 v73, v2
	v_mov_b32_e32 v14, v2
	v_mov_b32_e32 v15, v2
	v_mov_b32_e32 v16, v2
	v_mov_b32_e32 v17, v2
	v_mov_b32_e32 v78, v2
	v_mov_b32_e32 v79, v2
	v_mov_b32_e32 v80, v2
	v_mov_b32_e32 v81, v2
	v_mov_b32_e32 v22, v2
	v_mov_b32_e32 v23, v2
	v_mov_b32_e32 v24, v2
	v_mov_b32_e32 v25, v2
	v_mov_b32_e32 v86, v2
	v_mov_b32_e32 v87, v2
	v_mov_b32_e32 v88, v2
	v_mov_b32_e32 v89, v2
	v_mov_b32_e32 v30, v2
	v_mov_b32_e32 v31, v2
	v_mov_b32_e32 v32, v2
	v_mov_b32_e32 v33, v2
	v_mov_b32_e32 v94, v2
	v_mov_b32_e32 v95, v2
	v_mov_b32_e32 v96, v2
	v_mov_b32_e32 v97, v2
	v_mov_b32_e32 v34, v2
	v_mov_b32_e32 v35, v2
	v_mov_b32_e32 v36, v2
	v_mov_b32_e32 v37, v2
	v_mov_b32_e32 v98, v2
	v_mov_b32_e32 v99, v2
	v_mov_b32_e32 v100, v2
	v_mov_b32_e32 v101, v2
	v_mov_b32_e32 v42, v2
	v_mov_b32_e32 v43, v2
	v_mov_b32_e32 v44, v2
	v_mov_b32_e32 v45, v2
	v_mov_b32_e32 v106, v2
	v_mov_b32_e32 v107, v2
	v_mov_b32_e32 v108, v2
	v_mov_b32_e32 v109, v2
	v_mov_b32_e32 v50, v2
	v_mov_b32_e32 v51, v2
	v_mov_b32_e32 v52, v2
	v_mov_b32_e32 v53, v2
	v_mov_b32_e32 v114, v2
	v_mov_b32_e32 v115, v2
	v_mov_b32_e32 v116, v2
	v_mov_b32_e32 v117, v2
	v_mov_b32_e32 v58, v2
	v_mov_b32_e32 v59, v2
	v_mov_b32_e32 v60, v2
	v_mov_b32_e32 v61, v2
	v_mov_b32_e32 v146, v2
	v_mov_b32_e32 v147, v2
	v_mov_b32_e32 v148, v2
	v_mov_b32_e32 v149, v2
	v_mov_b32_e32 v38, v2
	v_mov_b32_e32 v39, v2
	v_mov_b32_e32 v40, v2
	v_mov_b32_e32 v41, v2
	v_mov_b32_e32 v102, v2
	v_mov_b32_e32 v103, v2
	v_mov_b32_e32 v104, v2
	v_mov_b32_e32 v105, v2
	v_mov_b32_e32 v46, v2
	v_mov_b32_e32 v47, v2
	v_mov_b32_e32 v48, v2
	v_mov_b32_e32 v49, v2
	v_mov_b32_e32 v110, v2
	v_mov_b32_e32 v111, v2
	v_mov_b32_e32 v112, v2
	v_mov_b32_e32 v113, v2
	v_mov_b32_e32 v54, v2
	v_mov_b32_e32 v55, v2
	v_mov_b32_e32 v56, v2
	v_mov_b32_e32 v57, v2
	v_mov_b32_e32 v118, v2
	v_mov_b32_e32 v119, v2
	v_mov_b32_e32 v120, v2
	v_mov_b32_e32 v121, v2
	v_mov_b32_e32 v62, v2
	v_mov_b32_e32 v63, v2
	v_mov_b32_e32 v64, v2
	v_mov_b32_e32 v65, v2
	v_mov_b32_e32 v126, v2
	v_mov_b32_e32 v127, v2
	v_mov_b32_e32 v128, v2
	v_mov_b32_e32 v129, v2
	s_lshl_b32 s100, s75, 8
	s_lshl_b32 s101, s85, 6
	s_add_i32 s100, s100, s101
	v_lshlrev_b32_e32 v240, 4, v181
	v_add3_u32 v240, s100, v185, v240
	v_bfe_i32 v241, v240, 7, 1
	v_and_b32_e32 v241, 0xb00, v241
	s_lshl_b32 s100, s22, 7
	v_add_u32_e32 v241, s100, v241
	s_movk_i32 s100, 0x7f
	v_and_or_b32 v241, v240, s100, v241
	v_ashrrev_i32_e32 v243, 31, v241
	v_mov_b32_e32 v242, v241
	v_lshlrev_b64 v[242:243], 2, v[242:243]
	v_lshl_add_u64 v[244:245], s[12:13], 0, v[242:243]
	v_lshl_add_u64 v[246:247], s[10:11], 0, v[242:243]
	v_ashrrev_i32_e32 v240, 8, v240
	s_movk_i32 s100, 0x5800
	v_mad_u64_u32 v[242:243], vcc, v240, s100, v[246:247]
	global_load_dword v248, v[242:243], off
	s_mov_b64 s[100:101], 0xb000
	v_cmp_eq_u32_e32 vcc, 0, v240
	v_lshl_add_u64 v[242:243], v[246:247], 0, s[100:101]
	s_nop 1
	v_cndmask_b32_e32 v242, v244, v242, vcc
	v_cndmask_b32_e32 v243, v245, v243, vcc
	global_load_dword v249, v[242:243], off

.LBB0_73:
	s_mov_b32 s30, s75
	v_mov_b32_e32 v133, v181
	s_mov_b32 s1, s85
	v_mov_b32_e32 v132, v185
	s_lshl_b32 s0, s30, 8
	s_lshl_b32 s23, s1, 6
	v_lshlrev_b32_e32 v122, 4, v133
	s_add_i32 s0, s0, s23
	v_add3_u32 v134, s0, v132, v122
	v_bfe_i32 v122, v134, 7, 1
	v_and_b32_e32 v122, 0xb00, v122
	s_lshl_b32 s0, s22, 7
	v_add_u32_e32 v122, s0, v122
	s_movk_i32 s22, 0x7f
	v_and_or_b32 v122, v134, s22, v122
	v_ashrrev_i32_e32 v123, 31, v122
	v_lshlrev_b64 v[124:125], 2, v[122:123]
	v_lshl_add_u64 v[122:123], s[12:13], 0, v[124:125]
	v_ashrrev_i32_e32 v135, 8, v134
	v_lshl_add_u64 v[124:125], s[10:11], 0, v[124:125]
	v_cmp_gt_i32_e32 vcc, 3, v135
	v_mov_b64_e32 v[130:131], v[122:123]
	s_and_saveexec_b64 s[22:23], vcc
	v_mul_hi_i32_i24_e32 v131, 0x5800, v135
	v_mul_i32_i24_e32 v130, 0x5800, v135
	v_lshl_add_u64 v[130:131], v[124:125], 0, v[130:131]
	s_or_b64 exec, exec, s[22:23]
	v_add_u32_e32 v131, 0x200, v134
	v_lshl_add_u32 v130, v134, 2, 0
	v_ashrrev_i32_e32 v131, 8, v131
	v_add_u32_e32 v130, 0x22400, v130
	v_cmp_gt_i32_e32 vcc, 3, v131
	s_and_saveexec_b64 s[22:23], vcc
	v_mul_hi_i32_i24_e32 v123, 0x5800, v131
	v_mul_i32_i24_e32 v122, 0x5800, v131
	v_lshl_add_u64 v[122:123], v[124:125], 0, v[122:123]
	s_or_b64 exec, exec, s[22:23]
	v_cmp_lt_i32_e32 vcc, 14, v132
	ds_write_b32 v130, v248
	ds_write_b32 v130, v249 offset:2048
	v_lshlrev_b32_e32 v122, 3, v133
	v_lshl_add_u32 v172, s1, 5, v122
	s_and_saveexec_b64 s[22:23], vcc
	s_xor_b64 s[22:23], exec, s[22:23]
	s_cbranch_execz .LBB0_81
	v_cmp_eq_u32_e32 vcc, 15, v132
	s_and_saveexec_b64 s[26:27], vcc
	s_cbranch_execz .LBB0_80
	s_lshl_b32 s1, s30, 11
	s_add_i32 s1, s1, 0
	s_add_i32 s1, s1, 0x20000
	v_lshl_add_u32 v122, v172, 2, s1
	ds_write_b128 v122, v[102:105] offset:1024
	ds_write_b128 v122, v[38:41] offset:1040
	ds_write_b128 v122, v[98:101] offset:1536
	ds_write_b128 v122, v[34:37] offset:1552

.LBB0_97:
	s_or_b64 exec, exec, s[22:23]
	s_cmp_gt_i32 s30, 0
	s_waitcnt lgkmcnt(0)
	s_barrier
	v_cmp_eq_u32_e64 s[42:43], 0, v132
	v_cmp_eq_u32_e64 s[40:41], 15, v132
	v_lshlrev_b32_e32 v230, 2, v172
	v_add_u32_e32 v230, 0x22400, v230
	s_lshl_b32 s100, s29, 8
	s_lshl_b32 s101, s30, 6
	s_add_i32 s100, s100, s101
	v_add_u32_e32 v231, s100, v132
	v_mov_b64_e32 v[232:233], s[16:17]
	v_mad_i64_i32 v[232:233], vcc, v231, s15, v[232:233]
	s_lshl_b64 s[100:101], s[0:1], 1
	v_lshl_add_u64 v[232:233], v[232:233], 0, s[100:101]
	v_lshlrev_b64 v[228:229], 1, v[172:173]
	v_lshl_add_u64 v[232:233], v[232:233], 0, v[228:229]
	ds_read_b128 v[190:193], v230 offset:0
	ds_read_b128 v[194:197], v230 offset:512
	ds_read_b128 v[198:201], v230 offset:1024
	ds_read_b128 v[208:211], v230 offset:1536
	ds_read_b128 v[212:215], v230 offset:2048
	ds_read_b128 v[216:219], v230 offset:2560
	ds_read_b128 v[220:223], v230 offset:3072
	ds_read_b128 v[224:227], v230 offset:3584
	s_cmp_eq_u32 s30, 0
	s_cbranch_scc1 .Lffn1c_1
	s_lshl_b32 s100, s30, 11
	s_sub_i32 s100, s100, 0x400
	v_add_u32_e32 v231, s100, v189
	ds_read_b128 v[130:133], v231 offset:0
	ds_read_b128 v[134:137], v231 offset:512
	s_branch .Lffn1c_2
.Lffn1c_1:
	v_mov_b32_e32 v130, 0
	v_mov_b32_e32 v131, 0
	v_mov_b32_e32 v132, 0
	v_mov_b32_e32 v133, 0
	v_mov_b32_e32 v134, 0
	v_mov_b32_e32 v135, 0
	v_mov_b32_e32 v136, 0
	v_mov_b32_e32 v137, 0
.Lffn1c_2:
	s_lshl_b32 s100, s30, 11
	s_add_i32 s100, s100, 0x800
	v_add_u32_e32 v231, s100, v189
	ds_read_b128 v[138:141], v231 offset:0
	ds_read_b128 v[142:145], v231 offset:512
	s_waitcnt lgkmcnt(0)
	v_cndmask_b32_e64 v150, v126, v130, s[40:41]
	v_cndmask_b32_e64 v151, v127, v131, s[40:41]
	v_cndmask_b32_e64 v152, v128, v132, s[40:41]
	v_cndmask_b32_e64 v153, v129, v133, s[40:41]
	v_cndmask_b32_e64 v154, v126, v118, s[42:43]
	v_cndmask_b32_e64 v155, v127, v119, s[42:43]
	v_cndmask_b32_e64 v156, v128, v120, s[42:43]
	v_cndmask_b32_e64 v157, v129, v121, s[42:43]
	v_fma_f32 v122, v126, v198, v220
	v_fma_f32 v123, v127, v199, v221
	v_fma_f32 v124, v128, v200, v222
	v_fma_f32 v125, v129, v201, v223
	v_fmac_f32_dpp v122, v150, v190 row_ror:1 row_mask:0xf bank_mask:0xf
	v_fmac_f32_dpp v123, v151, v191 row_ror:1 row_mask:0xf bank_mask:0xf
	v_fmac_f32_dpp v124, v152, v192 row_ror:1 row_mask:0xf bank_mask:0xf
	v_fmac_f32_dpp v125, v153, v193 row_ror:1 row_mask:0xf bank_mask:0xf
	v_fmac_f32_dpp v122, v154, v212 row_ror:15 row_mask:0xf bank_mask:0xf
	v_fmac_f32_dpp v123, v155, v213 row_ror:15 row_mask:0xf bank_mask:0xf
	v_fmac_f32_dpp v124, v156, v214 row_ror:15 row_mask:0xf bank_mask:0xf
	v_fmac_f32_dpp v125, v157, v215 row_ror:15 row_mask:0xf bank_mask:0xf
	v_cndmask_b32_e64 v150, v146, v134, s[40:41]
	v_cndmask_b32_e64 v151, v147, v135, s[40:41]
	v_cndmask_b32_e64 v152, v148, v136, s[40:41]
	v_cndmask_b32_e64 v153, v149, v137, s[40:41]
	v_cndmask_b32_e64 v154, v146, v114, s[42:43]
	v_cndmask_b32_e64 v155, v147, v115, s[42:43]
	v_cndmask_b32_e64 v156, v148, v116, s[42:43]
	v_cndmask_b32_e64 v157, v149, v117, s[42:43]
	v_fma_f32 v158, v146, v208, v224
	v_fma_f32 v159, v147, v209, v225
	v_fma_f32 v160, v148, v210, v226
	v_fma_f32 v161, v149, v211, v227
	v_fmac_f32_dpp v158, v150, v194 row_ror:1 row_mask:0xf bank_mask:0xf
	v_fmac_f32_dpp v159, v151, v195 row_ror:1 row_mask:0xf bank_mask:0xf
	v_fmac_f32_dpp v160, v152, v196 row_ror:1 row_mask:0xf bank_mask:0xf
	v_fmac_f32_dpp v161, v153, v197 row_ror:1 row_mask:0xf bank_mask:0xf
	v_fmac_f32_dpp v158, v154, v216 row_ror:15 row_mask:0xf bank_mask:0xf
	v_fmac_f32_dpp v159, v155, v217 row_ror:15 row_mask:0xf bank_mask:0xf
	v_fmac_f32_dpp v160, v156, v218 row_ror:15 row_mask:0xf bank_mask:0xf
	v_fmac_f32_dpp v161, v157, v219 row_ror:15 row_mask:0xf bank_mask:0xf
	s_lshl_b32 s100, s30, 11
	s_add_i32 s100, s100, 0xc00
	v_add_u32_e32 v231, s100, v189
	ds_read_b128 v[130:133], v231 offset:0
	ds_read_b128 v[134:137], v231 offset:512
	v_mul_f32_e32 v172, 0xbfb8aa3b, v122
	v_mul_f32_e32 v173, 0xbfb8aa3b, v123
	v_mul_f32_e32 v174, 0xbfb8aa3b, v124
	v_mul_f32_e32 v175, 0xbfb8aa3b, v125
	v_exp_f32_e32 v172, v172
	v_exp_f32_e32 v173, v173
	v_exp_f32_e32 v174, v174
	v_exp_f32_e32 v175, v175
	v_add_f32_e32 v172, 1.0, v172
	v_add_f32_e32 v173, 1.0, v173
	v_add_f32_e32 v174, 1.0, v174
	v_add_f32_e32 v175, 1.0, v175
	v_rcp_f32_e32 v172, v172
	v_rcp_f32_e32 v173, v173
	v_rcp_f32_e32 v174, v174
	v_rcp_f32_e32 v175, v175
	v_mov_b64_e32 v[234:235], v[232:233]
	v_mul_f32_e32 v172, v122, v172
	v_mul_f32_e32 v173, v123, v173
	v_mul_f32_e32 v174, v124, v174
	v_mul_f32_e32 v175, v125, v175
	v_mul_f32_e32 v172, v172, v158
	v_mul_f32_e32 v173, v173, v159
	v_mul_f32_e32 v174, v174, v160
	v_mul_f32_e32 v175, v175, v161
	v_cvt_pk_bf16_f32 v228, v172, v173
	v_cvt_pk_bf16_f32 v229, v174, v175
	global_store_dwordx2 v[234:235], v[228:229], off
	v_cndmask_b32_e64 v150, v118, v126, s[40:41]
	v_cndmask_b32_e64 v151, v119, v127, s[40:41]
	v_cndmask_b32_e64 v152, v120, v128, s[40:41]
	v_cndmask_b32_e64 v153, v121, v129, s[40:41]
	v_cndmask_b32_e64 v154, v118, v110, s[42:43]
	v_cndmask_b32_e64 v155, v119, v111, s[42:43]
	v_cndmask_b32_e64 v156, v120, v112, s[42:43]
	v_cndmask_b32_e64 v157, v121, v113, s[42:43]
	v_fma_f32 v122, v118, v198, v220
	v_fma_f32 v123, v119, v199, v221
	v_fma_f32 v124, v120, v200, v222
	v_fma_f32 v125, v121, v201, v223
	v_fmac_f32_dpp v122, v150, v190 row_ror:1 row_mask:0xf bank_mask:0xf
	v_fmac_f32_dpp v123, v151, v191 row_ror:1 row_mask:0xf bank_mask:0xf
	v_fmac_f32_dpp v124, v152, v192 row_ror:1 row_mask:0xf bank_mask:0xf
	v_fmac_f32_dpp v125, v153, v193 row_ror:1 row_mask:0xf bank_mask:0xf
	v_fmac_f32_dpp v122, v154, v212 row_ror:15 row_mask:0xf bank_mask:0xf
	v_fmac_f32_dpp v123, v155, v213 row_ror:15 row_mask:0xf bank_mask:0xf
	v_fmac_f32_dpp v124, v156, v214 row_ror:15 row_mask:0xf bank_mask:0xf
	v_fmac_f32_dpp v125, v157, v215 row_ror:15 row_mask:0xf bank_mask:0xf
	v_cndmask_b32_e64 v150, v114, v146, s[40:41]
	v_cndmask_b32_e64 v151, v115, v147, s[40:41]
	v_cndmask_b32_e64 v152, v116, v148, s[40:41]
	v_cndmask_b32_e64 v153, v117, v149, s[40:41]
	v_cndmask_b32_e64 v154, v114, v106, s[42:43]
	v_cndmask_b32_e64 v155, v115, v107, s[42:43]
	v_cndmask_b32_e64 v156, v116, v108, s[42:43]
	v_cndmask_b32_e64 v157, v117, v109, s[42:43]
	v_fma_f32 v158, v114, v208, v224
	v_fma_f32 v159, v115, v209, v225
	v_fma_f32 v160, v116, v210, v226
	v_fma_f32 v161, v117, v211, v227
	v_fmac_f32_dpp v158, v150, v194 row_ror:1 row_mask:0xf bank_mask:0xf
	v_fmac_f32_dpp v159, v151, v195 row_ror:1 row_mask:0xf bank_mask:0xf
	v_fmac_f32_dpp v160, v152, v196 row_ror:1 row_mask:0xf bank_mask:0xf
	v_fmac_f32_dpp v161, v153, v197 row_ror:1 row_mask:0xf bank_mask:0xf
	v_fmac_f32_dpp v158, v154, v216 row_ror:15 row_mask:0xf bank_mask:0xf
	v_fmac_f32_dpp v159, v155, v217 row_ror:15 row_mask:0xf bank_mask:0xf
	v_fmac_f32_dpp v160, v156, v218 row_ror:15 row_mask:0xf bank_mask:0xf
	v_fmac_f32_dpp v161, v157, v219 row_ror:15 row_mask:0xf bank_mask:0xf
	v_mul_f32_e32 v172, 0xbfb8aa3b, v122
	v_mul_f32_e32 v173, 0xbfb8aa3b, v123
	v_mul_f32_e32 v174, 0xbfb8aa3b, v124
	v_mul_f32_e32 v175, 0xbfb8aa3b, v125
	v_exp_f32_e32 v172, v172
	v_exp_f32_e32 v173, v173
	v_exp_f32_e32 v174, v174
	v_exp_f32_e32 v175, v175
	v_add_f32_e32 v172, 1.0, v172
	v_add_f32_e32 v173, 1.0, v173
	v_add_f32_e32 v174, 1.0, v174
	v_add_f32_e32 v175, 1.0, v175
	v_rcp_f32_e32 v172, v172
	v_rcp_f32_e32 v173, v173
	v_rcp_f32_e32 v174, v174
	v_rcp_f32_e32 v175, v175
	s_mov_b64 s[100:101], 0x16000
	v_lshl_add_u64 v[234:235], v[232:233], 0, s[100:101]
	v_mul_f32_e32 v172, v122, v172
	v_mul_f32_e32 v173, v123, v173
	v_mul_f32_e32 v174, v124, v174
	v_mul_f32_e32 v175, v125, v175
	v_mul_f32_e32 v172, v172, v158
	v_mul_f32_e32 v173, v173, v159
	v_mul_f32_e32 v174, v174, v160
	v_mul_f32_e32 v175, v175, v161
	v_cvt_pk_bf16_f32 v228, v172, v173
	v_cvt_pk_bf16_f32 v229, v174, v175
	global_store_dwordx2 v[234:235], v[228:229], off
	v_cndmask_b32_e64 v150, v110, v118, s[40:41]
	v_cndmask_b32_e64 v151, v111, v119, s[40:41]
	v_cndmask_b32_e64 v152, v112, v120, s[40:41]
	v_cndmask_b32_e64 v153, v113, v121, s[40:41]
	v_cndmask_b32_e64 v154, v110, v102, s[42:43]
	v_cndmask_b32_e64 v155, v111, v103, s[42:43]
	v_cndmask_b32_e64 v156, v112, v104, s[42:43]
	v_cndmask_b32_e64 v157, v113, v105, s[42:43]
	v_fma_f32 v122, v110, v198, v220
	v_fma_f32 v123, v111, v199, v221
	v_fma_f32 v124, v112, v200, v222
	v_fma_f32 v125, v113, v201, v223
	v_fmac_f32_dpp v122, v150, v190 row_ror:1 row_mask:0xf bank_mask:0xf
	v_fmac_f32_dpp v123, v151, v191 row_ror:1 row_mask:0xf bank_mask:0xf
	v_fmac_f32_dpp v124, v152, v192 row_ror:1 row_mask:0xf bank_mask:0xf
	v_fmac_f32_dpp v125, v153, v193 row_ror:1 row_mask:0xf bank_mask:0xf
	v_fmac_f32_dpp v122, v154, v212 row_ror:15 row_mask:0xf bank_mask:0xf
	v_fmac_f32_dpp v123, v155, v213 row_ror:15 row_mask:0xf bank_mask:0xf
	v_fmac_f32_dpp v124, v156, v214 row_ror:15 row_mask:0xf bank_mask:0xf
	v_fmac_f32_dpp v125, v157, v215 row_ror:15 row_mask:0xf bank_mask:0xf
	v_cndmask_b32_e64 v150, v106, v114, s[40:41]
	v_cndmask_b32_e64 v151, v107, v115, s[40:41]
	v_cndmask_b32_e64 v152, v108, v116, s[40:41]
	v_cndmask_b32_e64 v153, v109, v117, s[40:41]
	v_cndmask_b32_e64 v154, v106, v98, s[42:43]
	v_cndmask_b32_e64 v155, v107, v99, s[42:43]
	v_cndmask_b32_e64 v156, v108, v100, s[42:43]
	v_cndmask_b32_e64 v157, v109, v101, s[42:43]
	v_fma_f32 v158, v106, v208, v224
	v_fma_f32 v159, v107, v209, v225
	v_fma_f32 v160, v108, v210, v226
	v_fma_f32 v161, v109, v211, v227
	v_fmac_f32_dpp v158, v150, v194 row_ror:1 row_mask:0xf bank_mask:0xf
	v_fmac_f32_dpp v159, v151, v195 row_ror:1 row_mask:0xf bank_mask:0xf
	v_fmac_f32_dpp v160, v152, v196 row_ror:1 row_mask:0xf bank_mask:0xf
	v_fmac_f32_dpp v161, v153, v197 row_ror:1 row_mask:0xf bank_mask:0xf
	v_fmac_f32_dpp v158, v154, v216 row_ror:15 row_mask:0xf bank_mask:0xf
	v_fmac_f32_dpp v159, v155, v217 row_ror:15 row_mask:0xf bank_mask:0xf
	v_fmac_f32_dpp v160, v156, v218 row_ror:15 row_mask:0xf bank_mask:0xf
	v_fmac_f32_dpp v161, v157, v219 row_ror:15 row_mask:0xf bank_mask:0xf
	v_mul_f32_e32 v172, 0xbfb8aa3b, v122
	v_mul_f32_e32 v173, 0xbfb8aa3b, v123
	v_mul_f32_e32 v174, 0xbfb8aa3b, v124
	v_mul_f32_e32 v175, 0xbfb8aa3b, v125
	v_exp_f32_e32 v172, v172
	v_exp_f32_e32 v173, v173
	v_exp_f32_e32 v174, v174
	v_exp_f32_e32 v175, v175
	v_add_f32_e32 v172, 1.0, v172
	v_add_f32_e32 v173, 1.0, v173
	v_add_f32_e32 v174, 1.0, v174
	v_add_f32_e32 v175, 1.0, v175
	v_rcp_f32_e32 v172, v172
	v_rcp_f32_e32 v173, v173
	v_rcp_f32_e32 v174, v174
	v_rcp_f32_e32 v175, v175
	s_mov_b64 s[100:101], 0x2c000
	v_lshl_add_u64 v[234:235], v[232:233], 0, s[100:101]
	v_mul_f32_e32 v172, v122, v172
	v_mul_f32_e32 v173, v123, v173
	v_mul_f32_e32 v174, v124, v174
	v_mul_f32_e32 v175, v125, v175
	v_mul_f32_e32 v172, v172, v158
	v_mul_f32_e32 v173, v173, v159
	v_mul_f32_e32 v174, v174, v160
	v_mul_f32_e32 v175, v175, v161
	v_cvt_pk_bf16_f32 v228, v172, v173
	v_cvt_pk_bf16_f32 v229, v174, v175
	global_store_dwordx2 v[234:235], v[228:229], off
	s_waitcnt lgkmcnt(0)
	v_cndmask_b32_e64 v150, v102, v110, s[40:41]
	v_cndmask_b32_e64 v151, v103, v111, s[40:41]
	v_cndmask_b32_e64 v152, v104, v112, s[40:41]
	v_cndmask_b32_e64 v153, v105, v113, s[40:41]
	v_cndmask_b32_e64 v154, v102, v138, s[42:43]
	v_cndmask_b32_e64 v155, v103, v139, s[42:43]
	v_cndmask_b32_e64 v156, v104, v140, s[42:43]
	v_cndmask_b32_e64 v157, v105, v141, s[42:43]
	v_fma_f32 v122, v102, v198, v220
	v_fma_f32 v123, v103, v199, v221
	v_fma_f32 v124, v104, v200, v222
	v_fma_f32 v125, v105, v201, v223
	v_fmac_f32_dpp v122, v150, v190 row_ror:1 row_mask:0xf bank_mask:0xf
	v_fmac_f32_dpp v123, v151, v191 row_ror:1 row_mask:0xf bank_mask:0xf
	v_fmac_f32_dpp v124, v152, v192 row_ror:1 row_mask:0xf bank_mask:0xf
	v_fmac_f32_dpp v125, v153, v193 row_ror:1 row_mask:0xf bank_mask:0xf
	v_fmac_f32_dpp v122, v154, v212 row_ror:15 row_mask:0xf bank_mask:0xf
	v_fmac_f32_dpp v123, v155, v213 row_ror:15 row_mask:0xf bank_mask:0xf
	v_fmac_f32_dpp v124, v156, v214 row_ror:15 row_mask:0xf bank_mask:0xf
	v_fmac_f32_dpp v125, v157, v215 row_ror:15 row_mask:0xf bank_mask:0xf
	v_cndmask_b32_e64 v150, v98, v106, s[40:41]
	v_cndmask_b32_e64 v151, v99, v107, s[40:41]
	v_cndmask_b32_e64 v152, v100, v108, s[40:41]
	v_cndmask_b32_e64 v153, v101, v109, s[40:41]
	v_cndmask_b32_e64 v154, v98, v142, s[42:43]
	v_cndmask_b32_e64 v155, v99, v143, s[42:43]
	v_cndmask_b32_e64 v156, v100, v144, s[42:43]
	v_cndmask_b32_e64 v157, v101, v145, s[42:43]
	v_fma_f32 v158, v98, v208, v224
	v_fma_f32 v159, v99, v209, v225
	v_fma_f32 v160, v100, v210, v226
	v_fma_f32 v161, v101, v211, v227
	v_fmac_f32_dpp v158, v150, v194 row_ror:1 row_mask:0xf bank_mask:0xf
	v_fmac_f32_dpp v159, v151, v195 row_ror:1 row_mask:0xf bank_mask:0xf
	v_fmac_f32_dpp v160, v152, v196 row_ror:1 row_mask:0xf bank_mask:0xf
	v_fmac_f32_dpp v161, v153, v197 row_ror:1 row_mask:0xf bank_mask:0xf
	v_fmac_f32_dpp v158, v154, v216 row_ror:15 row_mask:0xf bank_mask:0xf
	v_fmac_f32_dpp v159, v155, v217 row_ror:15 row_mask:0xf bank_mask:0xf
	v_fmac_f32_dpp v160, v156, v218 row_ror:15 row_mask:0xf bank_mask:0xf
	v_fmac_f32_dpp v161, v157, v219 row_ror:15 row_mask:0xf bank_mask:0xf
	s_cmp_eq_u32 s30, 1
	s_cbranch_scc1 .Lffn1c_3
	s_lshl_b32 s100, s30, 11
	s_add_i32 s100, s100, 0x1800
	v_add_u32_e32 v231, s100, v189
	ds_read_b128 v[138:141], v231 offset:0
	ds_read_b128 v[142:145], v231 offset:512
	s_branch .Lffn1c_4
.Lffn1c_3:
	v_mov_b32_e32 v138, 0
	v_mov_b32_e32 v139, 0
	v_mov_b32_e32 v140, 0
	v_mov_b32_e32 v141, 0
	v_mov_b32_e32 v142, 0
	v_mov_b32_e32 v143, 0
	v_mov_b32_e32 v144, 0
	v_mov_b32_e32 v145, 0
.Lffn1c_4:
	ds_read_b128 v[126:129], v230 offset:16
	ds_read_b128 v[146:149], v230 offset:528
	ds_read_b128 v[118:121], v230 offset:1040
	ds_read_b128 v[114:117], v230 offset:1552
	ds_read_b128 v[110:113], v230 offset:2064
	ds_read_b128 v[106:109], v230 offset:2576
	ds_read_b128 v[102:105], v230 offset:3088
	ds_read_b128 v[98:101], v230 offset:3600
	v_mul_f32_e32 v172, 0xbfb8aa3b, v122
	v_mul_f32_e32 v173, 0xbfb8aa3b, v123
	v_mul_f32_e32 v174, 0xbfb8aa3b, v124
	v_mul_f32_e32 v175, 0xbfb8aa3b, v125
	v_exp_f32_e32 v172, v172
	v_exp_f32_e32 v173, v173
	v_exp_f32_e32 v174, v174
	v_exp_f32_e32 v175, v175
	v_add_f32_e32 v172, 1.0, v172
	v_add_f32_e32 v173, 1.0, v173
	v_add_f32_e32 v174, 1.0, v174
	v_add_f32_e32 v175, 1.0, v175
	v_rcp_f32_e32 v172, v172
	v_rcp_f32_e32 v173, v173
	v_rcp_f32_e32 v174, v174
	v_rcp_f32_e32 v175, v175
	s_mov_b64 s[100:101], 0x42000
	v_lshl_add_u64 v[234:235], v[232:233], 0, s[100:101]
	v_mul_f32_e32 v172, v122, v172
	v_mul_f32_e32 v173, v123, v173
	v_mul_f32_e32 v174, v124, v174
	v_mul_f32_e32 v175, v125, v175
	v_mul_f32_e32 v172, v172, v158
	v_mul_f32_e32 v173, v173, v159
	v_mul_f32_e32 v174, v174, v160
	v_mul_f32_e32 v175, v175, v161
	v_cvt_pk_bf16_f32 v228, v172, v173
	v_cvt_pk_bf16_f32 v229, v174, v175
	global_store_dwordx2 v[234:235], v[228:229], off
	s_waitcnt lgkmcnt(0)
	v_cndmask_b32_e64 v150, v94, v130, s[40:41]
	v_cndmask_b32_e64 v151, v95, v131, s[40:41]
	v_cndmask_b32_e64 v152, v96, v132, s[40:41]
	v_cndmask_b32_e64 v153, v97, v133, s[40:41]
	v_cndmask_b32_e64 v154, v94, v86, s[42:43]
	v_cndmask_b32_e64 v155, v95, v87, s[42:43]
	v_cndmask_b32_e64 v156, v96, v88, s[42:43]
	v_cndmask_b32_e64 v157, v97, v89, s[42:43]
	v_fma_f32 v122, v94, v198, v220
	v_fma_f32 v123, v95, v199, v221
	v_fma_f32 v124, v96, v200, v222
	v_fma_f32 v125, v97, v201, v223
	v_fmac_f32_dpp v122, v150, v190 row_ror:1 row_mask:0xf bank_mask:0xf
	v_fmac_f32_dpp v123, v151, v191 row_ror:1 row_mask:0xf bank_mask:0xf
	v_fmac_f32_dpp v124, v152, v192 row_ror:1 row_mask:0xf bank_mask:0xf
	v_fmac_f32_dpp v125, v153, v193 row_ror:1 row_mask:0xf bank_mask:0xf
	v_fmac_f32_dpp v122, v154, v212 row_ror:15 row_mask:0xf bank_mask:0xf
	v_fmac_f32_dpp v123, v155, v213 row_ror:15 row_mask:0xf bank_mask:0xf
	v_fmac_f32_dpp v124, v156, v214 row_ror:15 row_mask:0xf bank_mask:0xf
	v_fmac_f32_dpp v125, v157, v215 row_ror:15 row_mask:0xf bank_mask:0xf
	v_cndmask_b32_e64 v150, v90, v134, s[40:41]
	v_cndmask_b32_e64 v151, v91, v135, s[40:41]
	v_cndmask_b32_e64 v152, v92, v136, s[40:41]
	v_cndmask_b32_e64 v153, v93, v137, s[40:41]
	v_cndmask_b32_e64 v154, v90, v82, s[42:43]
	v_cndmask_b32_e64 v155, v91, v83, s[42:43]
	v_cndmask_b32_e64 v156, v92, v84, s[42:43]
	v_cndmask_b32_e64 v157, v93, v85, s[42:43]
	v_fma_f32 v158, v90, v208, v224
	v_fma_f32 v159, v91, v209, v225
	v_fma_f32 v160, v92, v210, v226
	v_fma_f32 v161, v93, v211, v227
	v_fmac_f32_dpp v158, v150, v194 row_ror:1 row_mask:0xf bank_mask:0xf
	v_fmac_f32_dpp v159, v151, v195 row_ror:1 row_mask:0xf bank_mask:0xf
	v_fmac_f32_dpp v160, v152, v196 row_ror:1 row_mask:0xf bank_mask:0xf
	v_fmac_f32_dpp v161, v153, v197 row_ror:1 row_mask:0xf bank_mask:0xf
	v_fmac_f32_dpp v158, v154, v216 row_ror:15 row_mask:0xf bank_mask:0xf
	v_fmac_f32_dpp v159, v155, v217 row_ror:15 row_mask:0xf bank_mask:0xf
	v_fmac_f32_dpp v160, v156, v218 row_ror:15 row_mask:0xf bank_mask:0xf
	v_fmac_f32_dpp v161, v157, v219 row_ror:15 row_mask:0xf bank_mask:0xf
	s_cmp_eq_u32 s30, 0
	s_cbranch_scc1 .Lffn1c_5
	s_lshl_b32 s100, s30, 11
	s_sub_i32 s100, s100, 0x400
	v_add_u32_e32 v231, s100, v189
	ds_read_b128 v[130:133], v231 offset:16
	ds_read_b128 v[134:137], v231 offset:528
	s_branch .Lffn1c_6

.Lffn1c_6:
	v_mul_f32_e32 v172, 0xbfb8aa3b, v122
	v_mul_f32_e32 v173, 0xbfb8aa3b, v123
	v_mul_f32_e32 v174, 0xbfb8aa3b, v124
	v_mul_f32_e32 v175, 0xbfb8aa3b, v125
	v_exp_f32_e32 v172, v172
	v_exp_f32_e32 v173, v173
	v_exp_f32_e32 v174, v174
	v_exp_f32_e32 v175, v175
	v_add_f32_e32 v172, 1.0, v172
	v_add_f32_e32 v173, 1.0, v173
	v_add_f32_e32 v174, 1.0, v174
	v_add_f32_e32 v175, 1.0, v175
	v_rcp_f32_e32 v172, v172
	v_rcp_f32_e32 v173, v173
	v_rcp_f32_e32 v174, v174
	v_rcp_f32_e32 v175, v175
	s_mov_b64 s[100:101], 0xb0000
	v_lshl_add_u64 v[234:235], v[232:233], 0, s[100:101]
	v_mul_f32_e32 v172, v122, v172
	v_mul_f32_e32 v173, v123, v173
	v_mul_f32_e32 v174, v124, v174
	v_mul_f32_e32 v175, v125, v175
	v_mul_f32_e32 v172, v172, v158
	v_mul_f32_e32 v173, v173, v159
	v_mul_f32_e32 v174, v174, v160
	v_mul_f32_e32 v175, v175, v161
	v_cvt_pk_bf16_f32 v228, v172, v173
	v_cvt_pk_bf16_f32 v229, v174, v175
	global_store_dwordx2 v[234:235], v[228:229], off
	v_cndmask_b32_e64 v150, v86, v94, s[40:41]
	v_cndmask_b32_e64 v151, v87, v95, s[40:41]
	v_cndmask_b32_e64 v152, v88, v96, s[40:41]
	v_cndmask_b32_e64 v153, v89, v97, s[40:41]
	v_cndmask_b32_e64 v154, v86, v78, s[42:43]
	v_cndmask_b32_e64 v155, v87, v79, s[42:43]
	v_cndmask_b32_e64 v156, v88, v80, s[42:43]
	v_cndmask_b32_e64 v157, v89, v81, s[42:43]
	v_fma_f32 v122, v86, v198, v220
	v_fma_f32 v123, v87, v199, v221
	v_fma_f32 v124, v88, v200, v222
	v_fma_f32 v125, v89, v201, v223
	v_fmac_f32_dpp v122, v150, v190 row_ror:1 row_mask:0xf bank_mask:0xf
	v_fmac_f32_dpp v123, v151, v191 row_ror:1 row_mask:0xf bank_mask:0xf
	v_fmac_f32_dpp v124, v152, v192 row_ror:1 row_mask:0xf bank_mask:0xf
	v_fmac_f32_dpp v125, v153, v193 row_ror:1 row_mask:0xf bank_mask:0xf
	v_fmac_f32_dpp v122, v154, v212 row_ror:15 row_mask:0xf bank_mask:0xf
	v_fmac_f32_dpp v123, v155, v213 row_ror:15 row_mask:0xf bank_mask:0xf
	v_fmac_f32_dpp v124, v156, v214 row_ror:15 row_mask:0xf bank_mask:0xf
	v_fmac_f32_dpp v125, v157, v215 row_ror:15 row_mask:0xf bank_mask:0xf
	v_cndmask_b32_e64 v150, v82, v90, s[40:41]
	v_cndmask_b32_e64 v151, v83, v91, s[40:41]
	v_cndmask_b32_e64 v152, v84, v92, s[40:41]
	v_cndmask_b32_e64 v153, v85, v93, s[40:41]
	v_cndmask_b32_e64 v154, v82, v74, s[42:43]
	v_cndmask_b32_e64 v155, v83, v75, s[42:43]
	v_cndmask_b32_e64 v156, v84, v76, s[42:43]
	v_cndmask_b32_e64 v157, v85, v77, s[42:43]
	v_fma_f32 v158, v82, v208, v224
	v_fma_f32 v159, v83, v209, v225
	v_fma_f32 v160, v84, v210, v226
	v_fma_f32 v161, v85, v211, v227
	v_fmac_f32_dpp v158, v150, v194 row_ror:1 row_mask:0xf bank_mask:0xf
	v_fmac_f32_dpp v159, v151, v195 row_ror:1 row_mask:0xf bank_mask:0xf
	v_fmac_f32_dpp v160, v152, v196 row_ror:1 row_mask:0xf bank_mask:0xf
	v_fmac_f32_dpp v161, v153, v197 row_ror:1 row_mask:0xf bank_mask:0xf
	v_fmac_f32_dpp v158, v154, v216 row_ror:15 row_mask:0xf bank_mask:0xf
	v_fmac_f32_dpp v159, v155, v217 row_ror:15 row_mask:0xf bank_mask:0xf
	v_fmac_f32_dpp v160, v156, v218 row_ror:15 row_mask:0xf bank_mask:0xf
	v_fmac_f32_dpp v161, v157, v219 row_ror:15 row_mask:0xf bank_mask:0xf
	v_mul_f32_e32 v172, 0xbfb8aa3b, v122
	v_mul_f32_e32 v173, 0xbfb8aa3b, v123
	v_mul_f32_e32 v174, 0xbfb8aa3b, v124
	v_mul_f32_e32 v175, 0xbfb8aa3b, v125
	v_exp_f32_e32 v172, v172
	v_exp_f32_e32 v173, v173
	v_exp_f32_e32 v174, v174
	v_exp_f32_e32 v175, v175
	v_add_f32_e32 v172, 1.0, v172
	v_add_f32_e32 v173, 1.0, v173
	v_add_f32_e32 v174, 1.0, v174
	v_add_f32_e32 v175, 1.0, v175
	v_rcp_f32_e32 v172, v172
	v_rcp_f32_e32 v173, v173
	v_rcp_f32_e32 v174, v174
	v_rcp_f32_e32 v175, v175
	s_mov_b64 s[100:101], 0xc6000
	v_lshl_add_u64 v[234:235], v[232:233], 0, s[100:101]
	v_mul_f32_e32 v172, v122, v172
	v_mul_f32_e32 v173, v123, v173
	v_mul_f32_e32 v174, v124, v174
	v_mul_f32_e32 v175, v125, v175
	v_mul_f32_e32 v172, v172, v158
	v_mul_f32_e32 v173, v173, v159
	v_mul_f32_e32 v174, v174, v160
	v_mul_f32_e32 v175, v175, v161
	v_cvt_pk_bf16_f32 v228, v172, v173
	v_cvt_pk_bf16_f32 v229, v174, v175
	global_store_dwordx2 v[234:235], v[228:229], off
	v_cndmask_b32_e64 v150, v78, v86, s[40:41]
	v_cndmask_b32_e64 v151, v79, v87, s[40:41]
	v_cndmask_b32_e64 v152, v80, v88, s[40:41]
	v_cndmask_b32_e64 v153, v81, v89, s[40:41]
	v_cndmask_b32_e64 v154, v78, v70, s[42:43]
	v_cndmask_b32_e64 v155, v79, v71, s[42:43]
	v_cndmask_b32_e64 v156, v80, v72, s[42:43]
	v_cndmask_b32_e64 v157, v81, v73, s[42:43]
	v_fma_f32 v122, v78, v198, v220
	v_fma_f32 v123, v79, v199, v221
	v_fma_f32 v124, v80, v200, v222
	v_fma_f32 v125, v81, v201, v223
	v_fmac_f32_dpp v122, v150, v190 row_ror:1 row_mask:0xf bank_mask:0xf
	v_fmac_f32_dpp v123, v151, v191 row_ror:1 row_mask:0xf bank_mask:0xf
	v_fmac_f32_dpp v124, v152, v192 row_ror:1 row_mask:0xf bank_mask:0xf
	v_fmac_f32_dpp v125, v153, v193 row_ror:1 row_mask:0xf bank_mask:0xf
	v_fmac_f32_dpp v122, v154, v212 row_ror:15 row_mask:0xf bank_mask:0xf
	v_fmac_f32_dpp v123, v155, v213 row_ror:15 row_mask:0xf bank_mask:0xf
	v_fmac_f32_dpp v124, v156, v214 row_ror:15 row_mask:0xf bank_mask:0xf
	v_fmac_f32_dpp v125, v157, v215 row_ror:15 row_mask:0xf bank_mask:0xf
	v_cndmask_b32_e64 v150, v74, v82, s[40:41]
	v_cndmask_b32_e64 v151, v75, v83, s[40:41]
	v_cndmask_b32_e64 v152, v76, v84, s[40:41]
	v_cndmask_b32_e64 v153, v77, v85, s[40:41]
	v_cndmask_b32_e64 v154, v74, v66, s[42:43]
	v_cndmask_b32_e64 v155, v75, v67, s[42:43]
	v_cndmask_b32_e64 v156, v76, v68, s[42:43]
	v_cndmask_b32_e64 v157, v77, v69, s[42:43]
	v_fma_f32 v158, v74, v208, v224
	v_fma_f32 v159, v75, v209, v225
	v_fma_f32 v160, v76, v210, v226
	v_fma_f32 v161, v77, v211, v227
	v_fmac_f32_dpp v158, v150, v194 row_ror:1 row_mask:0xf bank_mask:0xf
	v_fmac_f32_dpp v159, v151, v195 row_ror:1 row_mask:0xf bank_mask:0xf
	v_fmac_f32_dpp v160, v152, v196 row_ror:1 row_mask:0xf bank_mask:0xf
	v_fmac_f32_dpp v161, v153, v197 row_ror:1 row_mask:0xf bank_mask:0xf
	v_fmac_f32_dpp v158, v154, v216 row_ror:15 row_mask:0xf bank_mask:0xf
	v_fmac_f32_dpp v159, v155, v217 row_ror:15 row_mask:0xf bank_mask:0xf
	v_fmac_f32_dpp v160, v156, v218 row_ror:15 row_mask:0xf bank_mask:0xf
	v_fmac_f32_dpp v161, v157, v219 row_ror:15 row_mask:0xf bank_mask:0xf
	v_mul_f32_e32 v172, 0xbfb8aa3b, v122
	v_mul_f32_e32 v173, 0xbfb8aa3b, v123
	v_mul_f32_e32 v174, 0xbfb8aa3b, v124
	v_mul_f32_e32 v175, 0xbfb8aa3b, v125
	v_exp_f32_e32 v172, v172
	v_exp_f32_e32 v173, v173
	v_exp_f32_e32 v174, v174
	v_exp_f32_e32 v175, v175
	v_add_f32_e32 v172, 1.0, v172
	v_add_f32_e32 v173, 1.0, v173
	v_add_f32_e32 v174, 1.0, v174
	v_add_f32_e32 v175, 1.0, v175
	v_rcp_f32_e32 v172, v172
	v_rcp_f32_e32 v173, v173
	v_rcp_f32_e32 v174, v174
	v_rcp_f32_e32 v175, v175
	s_mov_b64 s[100:101], 0xdc000
	v_lshl_add_u64 v[234:235], v[232:233], 0, s[100:101]
	v_mul_f32_e32 v172, v122, v172
	v_mul_f32_e32 v173, v123, v173
	v_mul_f32_e32 v174, v124, v174
	v_mul_f32_e32 v175, v125, v175
	v_mul_f32_e32 v172, v172, v158
	v_mul_f32_e32 v173, v173, v159
	v_mul_f32_e32 v174, v174, v160
	v_mul_f32_e32 v175, v175, v161
	v_cvt_pk_bf16_f32 v228, v172, v173
	v_cvt_pk_bf16_f32 v229, v174, v175
	global_store_dwordx2 v[234:235], v[228:229], off
	s_waitcnt lgkmcnt(0)
	v_cndmask_b32_e64 v150, v70, v78, s[40:41]
	v_cndmask_b32_e64 v151, v71, v79, s[40:41]
	v_cndmask_b32_e64 v152, v72, v80, s[40:41]
	v_cndmask_b32_e64 v153, v73, v81, s[40:41]
	v_cndmask_b32_e64 v154, v70, v138, s[42:43]
	v_cndmask_b32_e64 v155, v71, v139, s[42:43]
	v_cndmask_b32_e64 v156, v72, v140, s[42:43]
	v_cndmask_b32_e64 v157, v73, v141, s[42:43]
	v_fma_f32 v122, v70, v198, v220
	v_fma_f32 v123, v71, v199, v221
	v_fma_f32 v124, v72, v200, v222
	v_fma_f32 v125, v73, v201, v223
	v_fmac_f32_dpp v122, v150, v190 row_ror:1 row_mask:0xf bank_mask:0xf
	v_fmac_f32_dpp v123, v151, v191 row_ror:1 row_mask:0xf bank_mask:0xf
	v_fmac_f32_dpp v124, v152, v192 row_ror:1 row_mask:0xf bank_mask:0xf
	v_fmac_f32_dpp v125, v153, v193 row_ror:1 row_mask:0xf bank_mask:0xf
	v_fmac_f32_dpp v122, v154, v212 row_ror:15 row_mask:0xf bank_mask:0xf
	v_fmac_f32_dpp v123, v155, v213 row_ror:15 row_mask:0xf bank_mask:0xf
	v_fmac_f32_dpp v124, v156, v214 row_ror:15 row_mask:0xf bank_mask:0xf
	v_fmac_f32_dpp v125, v157, v215 row_ror:15 row_mask:0xf bank_mask:0xf
	v_cndmask_b32_e64 v150, v66, v74, s[40:41]
	v_cndmask_b32_e64 v151, v67, v75, s[40:41]
	v_cndmask_b32_e64 v152, v68, v76, s[40:41]
	v_cndmask_b32_e64 v153, v69, v77, s[40:41]
	v_cndmask_b32_e64 v154, v66, v142, s[42:43]
	v_cndmask_b32_e64 v155, v67, v143, s[42:43]
	v_cndmask_b32_e64 v156, v68, v144, s[42:43]
	v_cndmask_b32_e64 v157, v69, v145, s[42:43]
	v_fma_f32 v158, v66, v208, v224
	v_fma_f32 v159, v67, v209, v225
	v_fma_f32 v160, v68, v210, v226
	v_fma_f32 v161, v69, v211, v227
	v_fmac_f32_dpp v158, v150, v194 row_ror:1 row_mask:0xf bank_mask:0xf
	v_fmac_f32_dpp v159, v151, v195 row_ror:1 row_mask:0xf bank_mask:0xf
	v_fmac_f32_dpp v160, v152, v196 row_ror:1 row_mask:0xf bank_mask:0xf
	v_fmac_f32_dpp v161, v153, v197 row_ror:1 row_mask:0xf bank_mask:0xf
	v_fmac_f32_dpp v158, v154, v216 row_ror:15 row_mask:0xf bank_mask:0xf
	v_fmac_f32_dpp v159, v155, v217 row_ror:15 row_mask:0xf bank_mask:0xf
	v_fmac_f32_dpp v160, v156, v218 row_ror:15 row_mask:0xf bank_mask:0xf
	v_fmac_f32_dpp v161, v157, v219 row_ror:15 row_mask:0xf bank_mask:0xf
	s_lshl_b32 s100, s30, 11
	s_add_i32 s100, s100, 0x800
	v_add_u32_e32 v231, s100, v189
	ds_read_b128 v[138:141], v231 offset:16
	ds_read_b128 v[142:145], v231 offset:528
	v_mul_f32_e32 v172, 0xbfb8aa3b, v122
	v_mul_f32_e32 v173, 0xbfb8aa3b, v123
	v_mul_f32_e32 v174, 0xbfb8aa3b, v124
	v_mul_f32_e32 v175, 0xbfb8aa3b, v125
	v_exp_f32_e32 v172, v172
	v_exp_f32_e32 v173, v173
	v_exp_f32_e32 v174, v174
	v_exp_f32_e32 v175, v175
	v_add_f32_e32 v172, 1.0, v172
	v_add_f32_e32 v173, 1.0, v173
	v_add_f32_e32 v174, 1.0, v174
	v_add_f32_e32 v175, 1.0, v175
	v_rcp_f32_e32 v172, v172
	v_rcp_f32_e32 v173, v173
	v_rcp_f32_e32 v174, v174
	v_rcp_f32_e32 v175, v175
	s_mov_b64 s[100:101], 0xf2000
	v_lshl_add_u64 v[234:235], v[232:233], 0, s[100:101]
	v_mul_f32_e32 v172, v122, v172
	v_mul_f32_e32 v173, v123, v173
	v_mul_f32_e32 v174, v124, v174
	v_mul_f32_e32 v175, v125, v175
	v_mul_f32_e32 v172, v172, v158
	v_mul_f32_e32 v173, v173, v159
	v_mul_f32_e32 v174, v174, v160
	v_mul_f32_e32 v175, v175, v161
	v_cvt_pk_bf16_f32 v228, v172, v173
	v_cvt_pk_bf16_f32 v229, v174, v175
	global_store_dwordx2 v[234:235], v[228:229], off
	s_waitcnt lgkmcnt(0)
	v_cndmask_b32_e64 v150, v62, v130, s[40:41]
	v_cndmask_b32_e64 v151, v63, v131, s[40:41]
	v_cndmask_b32_e64 v152, v64, v132, s[40:41]
	v_cndmask_b32_e64 v153, v65, v133, s[40:41]
	v_cndmask_b32_e64 v154, v62, v54, s[42:43]
	v_cndmask_b32_e64 v155, v63, v55, s[42:43]
	v_cndmask_b32_e64 v156, v64, v56, s[42:43]
	v_cndmask_b32_e64 v157, v65, v57, s[42:43]
	v_fma_f32 v122, v62, v118, v102
	v_fma_f32 v123, v63, v119, v103
	v_fma_f32 v124, v64, v120, v104
	v_fma_f32 v125, v65, v121, v105
	v_fmac_f32_dpp v122, v150, v126 row_ror:1 row_mask:0xf bank_mask:0xf
	v_fmac_f32_dpp v123, v151, v127 row_ror:1 row_mask:0xf bank_mask:0xf
	v_fmac_f32_dpp v124, v152, v128 row_ror:1 row_mask:0xf bank_mask:0xf
	v_fmac_f32_dpp v125, v153, v129 row_ror:1 row_mask:0xf bank_mask:0xf
	v_fmac_f32_dpp v122, v154, v110 row_ror:15 row_mask:0xf bank_mask:0xf
	v_fmac_f32_dpp v123, v155, v111 row_ror:15 row_mask:0xf bank_mask:0xf
	v_fmac_f32_dpp v124, v156, v112 row_ror:15 row_mask:0xf bank_mask:0xf
	v_fmac_f32_dpp v125, v157, v113 row_ror:15 row_mask:0xf bank_mask:0xf
	v_cndmask_b32_e64 v150, v58, v134, s[40:41]
	v_cndmask_b32_e64 v151, v59, v135, s[40:41]
	v_cndmask_b32_e64 v152, v60, v136, s[40:41]
	v_cndmask_b32_e64 v153, v61, v137, s[40:41]
	v_cndmask_b32_e64 v154, v58, v50, s[42:43]
	v_cndmask_b32_e64 v155, v59, v51, s[42:43]
	v_cndmask_b32_e64 v156, v60, v52, s[42:43]
	v_cndmask_b32_e64 v157, v61, v53, s[42:43]
	v_fma_f32 v158, v58, v114, v98
	v_fma_f32 v159, v59, v115, v99
	v_fma_f32 v160, v60, v116, v100
	v_fma_f32 v161, v61, v117, v101
	v_fmac_f32_dpp v158, v150, v146 row_ror:1 row_mask:0xf bank_mask:0xf
	v_fmac_f32_dpp v159, v151, v147 row_ror:1 row_mask:0xf bank_mask:0xf
	v_fmac_f32_dpp v160, v152, v148 row_ror:1 row_mask:0xf bank_mask:0xf
	v_fmac_f32_dpp v161, v153, v149 row_ror:1 row_mask:0xf bank_mask:0xf
	v_fmac_f32_dpp v158, v154, v106 row_ror:15 row_mask:0xf bank_mask:0xf
	v_fmac_f32_dpp v159, v155, v107 row_ror:15 row_mask:0xf bank_mask:0xf
	v_fmac_f32_dpp v160, v156, v108 row_ror:15 row_mask:0xf bank_mask:0xf
	v_fmac_f32_dpp v161, v157, v109 row_ror:15 row_mask:0xf bank_mask:0xf
	s_lshl_b32 s100, s30, 11
	s_add_i32 s100, s100, 0xc00
	v_add_u32_e32 v231, s100, v189
	ds_read_b128 v[130:133], v231 offset:16
	ds_read_b128 v[134:137], v231 offset:528
	v_mul_f32_e32 v172, 0xbfb8aa3b, v122
	v_mul_f32_e32 v173, 0xbfb8aa3b, v123
	v_mul_f32_e32 v174, 0xbfb8aa3b, v124
	v_mul_f32_e32 v175, 0xbfb8aa3b, v125
	v_exp_f32_e32 v172, v172
	v_exp_f32_e32 v173, v173
	v_exp_f32_e32 v174, v174
	v_exp_f32_e32 v175, v175
	v_add_f32_e32 v172, 1.0, v172
	v_add_f32_e32 v173, 1.0, v173
	v_add_f32_e32 v174, 1.0, v174
	v_add_f32_e32 v175, 1.0, v175
	v_rcp_f32_e32 v172, v172
	v_rcp_f32_e32 v173, v173
	v_rcp_f32_e32 v174, v174
	v_rcp_f32_e32 v175, v175
	v_mov_b64_e32 v[234:235], v[232:233]
	v_mul_f32_e32 v172, v122, v172
	v_mul_f32_e32 v173, v123, v173
	v_mul_f32_e32 v174, v124, v174
	v_mul_f32_e32 v175, v125, v175
	v_mul_f32_e32 v172, v172, v158
	v_mul_f32_e32 v173, v173, v159
	v_mul_f32_e32 v174, v174, v160
	v_mul_f32_e32 v175, v175, v161
	v_cvt_pk_bf16_f32 v228, v172, v173
	v_cvt_pk_bf16_f32 v229, v174, v175
	global_store_dwordx2 v[234:235], v[228:229], off offset:8
	v_cndmask_b32_e64 v150, v54, v62, s[40:41]
	v_cndmask_b32_e64 v151, v55, v63, s[40:41]
	v_cndmask_b32_e64 v152, v56, v64, s[40:41]
	v_cndmask_b32_e64 v153, v57, v65, s[40:41]
	v_cndmask_b32_e64 v154, v54, v46, s[42:43]
	v_cndmask_b32_e64 v155, v55, v47, s[42:43]
	v_cndmask_b32_e64 v156, v56, v48, s[42:43]
	v_cndmask_b32_e64 v157, v57, v49, s[42:43]
	v_fma_f32 v122, v54, v118, v102
	v_fma_f32 v123, v55, v119, v103
	v_fma_f32 v124, v56, v120, v104
	v_fma_f32 v125, v57, v121, v105
	v_fmac_f32_dpp v122, v150, v126 row_ror:1 row_mask:0xf bank_mask:0xf
	v_fmac_f32_dpp v123, v151, v127 row_ror:1 row_mask:0xf bank_mask:0xf
	v_fmac_f32_dpp v124, v152, v128 row_ror:1 row_mask:0xf bank_mask:0xf
	v_fmac_f32_dpp v125, v153, v129 row_ror:1 row_mask:0xf bank_mask:0xf
	v_fmac_f32_dpp v122, v154, v110 row_ror:15 row_mask:0xf bank_mask:0xf
	v_fmac_f32_dpp v123, v155, v111 row_ror:15 row_mask:0xf bank_mask:0xf
	v_fmac_f32_dpp v124, v156, v112 row_ror:15 row_mask:0xf bank_mask:0xf
	v_fmac_f32_dpp v125, v157, v113 row_ror:15 row_mask:0xf bank_mask:0xf
	v_cndmask_b32_e64 v150, v50, v58, s[40:41]
	v_cndmask_b32_e64 v151, v51, v59, s[40:41]
	v_cndmask_b32_e64 v152, v52, v60, s[40:41]
	v_cndmask_b32_e64 v153, v53, v61, s[40:41]
	v_cndmask_b32_e64 v154, v50, v42, s[42:43]
	v_cndmask_b32_e64 v155, v51, v43, s[42:43]
	v_cndmask_b32_e64 v156, v52, v44, s[42:43]
	v_cndmask_b32_e64 v157, v53, v45, s[42:43]
	v_fma_f32 v158, v50, v114, v98
	v_fma_f32 v159, v51, v115, v99
	v_fma_f32 v160, v52, v116, v100
	v_fma_f32 v161, v53, v117, v101
	v_fmac_f32_dpp v158, v150, v146 row_ror:1 row_mask:0xf bank_mask:0xf
	v_fmac_f32_dpp v159, v151, v147 row_ror:1 row_mask:0xf bank_mask:0xf
	v_fmac_f32_dpp v160, v152, v148 row_ror:1 row_mask:0xf bank_mask:0xf
	v_fmac_f32_dpp v161, v153, v149 row_ror:1 row_mask:0xf bank_mask:0xf
	v_fmac_f32_dpp v158, v154, v106 row_ror:15 row_mask:0xf bank_mask:0xf
	v_fmac_f32_dpp v159, v155, v107 row_ror:15 row_mask:0xf bank_mask:0xf
	v_fmac_f32_dpp v160, v156, v108 row_ror:15 row_mask:0xf bank_mask:0xf
	v_fmac_f32_dpp v161, v157, v109 row_ror:15 row_mask:0xf bank_mask:0xf
	v_mul_f32_e32 v172, 0xbfb8aa3b, v122
	v_mul_f32_e32 v173, 0xbfb8aa3b, v123
	v_mul_f32_e32 v174, 0xbfb8aa3b, v124
	v_mul_f32_e32 v175, 0xbfb8aa3b, v125
	v_exp_f32_e32 v172, v172
	v_exp_f32_e32 v173, v173
	v_exp_f32_e32 v174, v174
	v_exp_f32_e32 v175, v175
	v_add_f32_e32 v172, 1.0, v172
	v_add_f32_e32 v173, 1.0, v173
	v_add_f32_e32 v174, 1.0, v174
	v_add_f32_e32 v175, 1.0, v175
	v_rcp_f32_e32 v172, v172
	v_rcp_f32_e32 v173, v173
	v_rcp_f32_e32 v174, v174
	v_rcp_f32_e32 v175, v175
	s_mov_b64 s[100:101], 0x16000
	v_lshl_add_u64 v[234:235], v[232:233], 0, s[100:101]
	v_mul_f32_e32 v172, v122, v172
	v_mul_f32_e32 v173, v123, v173
	v_mul_f32_e32 v174, v124, v174
	v_mul_f32_e32 v175, v125, v175
	v_mul_f32_e32 v172, v172, v158
	v_mul_f32_e32 v173, v173, v159
	v_mul_f32_e32 v174, v174, v160
	v_mul_f32_e32 v175, v175, v161
	v_cvt_pk_bf16_f32 v228, v172, v173
	v_cvt_pk_bf16_f32 v229, v174, v175
	global_store_dwordx2 v[234:235], v[228:229], off offset:8
	v_cndmask_b32_e64 v150, v46, v54, s[40:41]
	v_cndmask_b32_e64 v151, v47, v55, s[40:41]
	v_cndmask_b32_e64 v152, v48, v56, s[40:41]
	v_cndmask_b32_e64 v153, v49, v57, s[40:41]
	v_cndmask_b32_e64 v154, v46, v38, s[42:43]
	v_cndmask_b32_e64 v155, v47, v39, s[42:43]
	v_cndmask_b32_e64 v156, v48, v40, s[42:43]
	v_cndmask_b32_e64 v157, v49, v41, s[42:43]
	v_fma_f32 v122, v46, v118, v102
	v_fma_f32 v123, v47, v119, v103
	v_fma_f32 v124, v48, v120, v104
	v_fma_f32 v125, v49, v121, v105
	v_fmac_f32_dpp v122, v150, v126 row_ror:1 row_mask:0xf bank_mask:0xf
	v_fmac_f32_dpp v123, v151, v127 row_ror:1 row_mask:0xf bank_mask:0xf
	v_fmac_f32_dpp v124, v152, v128 row_ror:1 row_mask:0xf bank_mask:0xf
	v_fmac_f32_dpp v125, v153, v129 row_ror:1 row_mask:0xf bank_mask:0xf
	v_fmac_f32_dpp v122, v154, v110 row_ror:15 row_mask:0xf bank_mask:0xf
	v_fmac_f32_dpp v123, v155, v111 row_ror:15 row_mask:0xf bank_mask:0xf
	v_fmac_f32_dpp v124, v156, v112 row_ror:15 row_mask:0xf bank_mask:0xf
	v_fmac_f32_dpp v125, v157, v113 row_ror:15 row_mask:0xf bank_mask:0xf
	v_cndmask_b32_e64 v150, v42, v50, s[40:41]
	v_cndmask_b32_e64 v151, v43, v51, s[40:41]
	v_cndmask_b32_e64 v152, v44, v52, s[40:41]
	v_cndmask_b32_e64 v153, v45, v53, s[40:41]
	v_cndmask_b32_e64 v154, v42, v34, s[42:43]
	v_cndmask_b32_e64 v155, v43, v35, s[42:43]
	v_cndmask_b32_e64 v156, v44, v36, s[42:43]
	v_cndmask_b32_e64 v157, v45, v37, s[42:43]
	v_fma_f32 v158, v42, v114, v98
	v_fma_f32 v159, v43, v115, v99
	v_fma_f32 v160, v44, v116, v100
	v_fma_f32 v161, v45, v117, v101
	v_fmac_f32_dpp v158, v150, v146 row_ror:1 row_mask:0xf bank_mask:0xf
	v_fmac_f32_dpp v159, v151, v147 row_ror:1 row_mask:0xf bank_mask:0xf
	v_fmac_f32_dpp v160, v152, v148 row_ror:1 row_mask:0xf bank_mask:0xf
	v_fmac_f32_dpp v161, v153, v149 row_ror:1 row_mask:0xf bank_mask:0xf
	v_fmac_f32_dpp v158, v154, v106 row_ror:15 row_mask:0xf bank_mask:0xf
	v_fmac_f32_dpp v159, v155, v107 row_ror:15 row_mask:0xf bank_mask:0xf
	v_fmac_f32_dpp v160, v156, v108 row_ror:15 row_mask:0xf bank_mask:0xf
	v_fmac_f32_dpp v161, v157, v109 row_ror:15 row_mask:0xf bank_mask:0xf
	v_mul_f32_e32 v172, 0xbfb8aa3b, v122
	v_mul_f32_e32 v173, 0xbfb8aa3b, v123
	v_mul_f32_e32 v174, 0xbfb8aa3b, v124
	v_mul_f32_e32 v175, 0xbfb8aa3b, v125
	v_exp_f32_e32 v172, v172
	v_exp_f32_e32 v173, v173
	v_exp_f32_e32 v174, v174
	v_exp_f32_e32 v175, v175
	v_add_f32_e32 v172, 1.0, v172
	v_add_f32_e32 v173, 1.0, v173
	v_add_f32_e32 v174, 1.0, v174
	v_add_f32_e32 v175, 1.0, v175
	v_rcp_f32_e32 v172, v172
	v_rcp_f32_e32 v173, v173
	v_rcp_f32_e32 v174, v174
	v_rcp_f32_e32 v175, v175
	s_mov_b64 s[100:101], 0x2c000
	v_lshl_add_u64 v[234:235], v[232:233], 0, s[100:101]
	v_mul_f32_e32 v172, v122, v172
	v_mul_f32_e32 v173, v123, v173
	v_mul_f32_e32 v174, v124, v174
	v_mul_f32_e32 v175, v125, v175
	v_mul_f32_e32 v172, v172, v158
	v_mul_f32_e32 v173, v173, v159
	v_mul_f32_e32 v174, v174, v160
	v_mul_f32_e32 v175, v175, v161
	v_cvt_pk_bf16_f32 v228, v172, v173
	v_cvt_pk_bf16_f32 v229, v174, v175
	global_store_dwordx2 v[234:235], v[228:229], off offset:8
	s_waitcnt lgkmcnt(0)
	v_cndmask_b32_e64 v150, v38, v46, s[40:41]
	v_cndmask_b32_e64 v151, v39, v47, s[40:41]
	v_cndmask_b32_e64 v152, v40, v48, s[40:41]
	v_cndmask_b32_e64 v153, v41, v49, s[40:41]
	v_cndmask_b32_e64 v154, v38, v138, s[42:43]
	v_cndmask_b32_e64 v155, v39, v139, s[42:43]
	v_cndmask_b32_e64 v156, v40, v140, s[42:43]
	v_cndmask_b32_e64 v157, v41, v141, s[42:43]
	v_fma_f32 v122, v38, v118, v102
	v_fma_f32 v123, v39, v119, v103
	v_fma_f32 v124, v40, v120, v104
	v_fma_f32 v125, v41, v121, v105
	v_fmac_f32_dpp v122, v150, v126 row_ror:1 row_mask:0xf bank_mask:0xf
	v_fmac_f32_dpp v123, v151, v127 row_ror:1 row_mask:0xf bank_mask:0xf
	v_fmac_f32_dpp v124, v152, v128 row_ror:1 row_mask:0xf bank_mask:0xf
	v_fmac_f32_dpp v125, v153, v129 row_ror:1 row_mask:0xf bank_mask:0xf
	v_fmac_f32_dpp v122, v154, v110 row_ror:15 row_mask:0xf bank_mask:0xf
	v_fmac_f32_dpp v123, v155, v111 row_ror:15 row_mask:0xf bank_mask:0xf
	v_fmac_f32_dpp v124, v156, v112 row_ror:15 row_mask:0xf bank_mask:0xf
	v_fmac_f32_dpp v125, v157, v113 row_ror:15 row_mask:0xf bank_mask:0xf
	v_cndmask_b32_e64 v150, v34, v42, s[40:41]
	v_cndmask_b32_e64 v151, v35, v43, s[40:41]
	v_cndmask_b32_e64 v152, v36, v44, s[40:41]
	v_cndmask_b32_e64 v153, v37, v45, s[40:41]
	v_cndmask_b32_e64 v154, v34, v142, s[42:43]
	v_cndmask_b32_e64 v155, v35, v143, s[42:43]
	v_cndmask_b32_e64 v156, v36, v144, s[42:43]
	v_cndmask_b32_e64 v157, v37, v145, s[42:43]
	v_fma_f32 v158, v34, v114, v98
	v_fma_f32 v159, v35, v115, v99
	v_fma_f32 v160, v36, v116, v100
	v_fma_f32 v161, v37, v117, v101
	v_fmac_f32_dpp v158, v150, v146 row_ror:1 row_mask:0xf bank_mask:0xf
	v_fmac_f32_dpp v159, v151, v147 row_ror:1 row_mask:0xf bank_mask:0xf
	v_fmac_f32_dpp v160, v152, v148 row_ror:1 row_mask:0xf bank_mask:0xf
	v_fmac_f32_dpp v161, v153, v149 row_ror:1 row_mask:0xf bank_mask:0xf
	v_fmac_f32_dpp v158, v154, v106 row_ror:15 row_mask:0xf bank_mask:0xf
	v_fmac_f32_dpp v159, v155, v107 row_ror:15 row_mask:0xf bank_mask:0xf
	v_fmac_f32_dpp v160, v156, v108 row_ror:15 row_mask:0xf bank_mask:0xf
	v_fmac_f32_dpp v161, v157, v109 row_ror:15 row_mask:0xf bank_mask:0xf
	s_cmp_eq_u32 s30, 1
	s_cbranch_scc1 .Lffn1c_7
	s_lshl_b32 s100, s30, 11
	s_add_i32 s100, s100, 0x1800
	v_add_u32_e32 v231, s100, v189
	ds_read_b128 v[138:141], v231 offset:16
	ds_read_b128 v[142:145], v231 offset:528
	s_branch .Lffn1c_8

.Lffn1c_8:
	v_mul_f32_e32 v172, 0xbfb8aa3b, v122
	v_mul_f32_e32 v173, 0xbfb8aa3b, v123
	v_mul_f32_e32 v174, 0xbfb8aa3b, v124
	v_mul_f32_e32 v175, 0xbfb8aa3b, v125
	v_exp_f32_e32 v172, v172
	v_exp_f32_e32 v173, v173
	v_exp_f32_e32 v174, v174
	v_exp_f32_e32 v175, v175
	v_add_f32_e32 v172, 1.0, v172
	v_add_f32_e32 v173, 1.0, v173
	v_add_f32_e32 v174, 1.0, v174
	v_add_f32_e32 v175, 1.0, v175
	v_rcp_f32_e32 v172, v172
	v_rcp_f32_e32 v173, v173
	v_rcp_f32_e32 v174, v174
	v_rcp_f32_e32 v175, v175
	s_mov_b64 s[100:101], 0x42000
	v_lshl_add_u64 v[234:235], v[232:233], 0, s[100:101]
	v_mul_f32_e32 v172, v122, v172
	v_mul_f32_e32 v173, v123, v173
	v_mul_f32_e32 v174, v124, v174
	v_mul_f32_e32 v175, v125, v175
	v_mul_f32_e32 v172, v172, v158
	v_mul_f32_e32 v173, v173, v159
	v_mul_f32_e32 v174, v174, v160
	v_mul_f32_e32 v175, v175, v161
	v_cvt_pk_bf16_f32 v228, v172, v173
	v_cvt_pk_bf16_f32 v229, v174, v175
	global_store_dwordx2 v[234:235], v[228:229], off offset:8
	s_waitcnt lgkmcnt(0)
	v_cndmask_b32_e64 v150, v30, v130, s[40:41]
	v_cndmask_b32_e64 v151, v31, v131, s[40:41]
	v_cndmask_b32_e64 v152, v32, v132, s[40:41]
	v_cndmask_b32_e64 v153, v33, v133, s[40:41]
	v_cndmask_b32_e64 v154, v30, v22, s[42:43]
	v_cndmask_b32_e64 v155, v31, v23, s[42:43]
	v_cndmask_b32_e64 v156, v32, v24, s[42:43]
	v_cndmask_b32_e64 v157, v33, v25, s[42:43]
	v_fma_f32 v122, v30, v118, v102
	v_fma_f32 v123, v31, v119, v103
	v_fma_f32 v124, v32, v120, v104
	v_fma_f32 v125, v33, v121, v105
	v_fmac_f32_dpp v122, v150, v126 row_ror:1 row_mask:0xf bank_mask:0xf
	v_fmac_f32_dpp v123, v151, v127 row_ror:1 row_mask:0xf bank_mask:0xf
	v_fmac_f32_dpp v124, v152, v128 row_ror:1 row_mask:0xf bank_mask:0xf
	v_fmac_f32_dpp v125, v153, v129 row_ror:1 row_mask:0xf bank_mask:0xf
	v_fmac_f32_dpp v122, v154, v110 row_ror:15 row_mask:0xf bank_mask:0xf
	v_fmac_f32_dpp v123, v155, v111 row_ror:15 row_mask:0xf bank_mask:0xf
	v_fmac_f32_dpp v124, v156, v112 row_ror:15 row_mask:0xf bank_mask:0xf
	v_fmac_f32_dpp v125, v157, v113 row_ror:15 row_mask:0xf bank_mask:0xf
	v_cndmask_b32_e64 v150, v26, v134, s[40:41]
	v_cndmask_b32_e64 v151, v27, v135, s[40:41]
	v_cndmask_b32_e64 v152, v28, v136, s[40:41]
	v_cndmask_b32_e64 v153, v29, v137, s[40:41]
	v_cndmask_b32_e64 v154, v26, v18, s[42:43]
	v_cndmask_b32_e64 v155, v27, v19, s[42:43]
	v_cndmask_b32_e64 v156, v28, v20, s[42:43]
	v_cndmask_b32_e64 v157, v29, v21, s[42:43]
	v_fma_f32 v158, v26, v114, v98
	v_fma_f32 v159, v27, v115, v99
	v_fma_f32 v160, v28, v116, v100
	v_fma_f32 v161, v29, v117, v101
	v_fmac_f32_dpp v158, v150, v146 row_ror:1 row_mask:0xf bank_mask:0xf
	v_fmac_f32_dpp v159, v151, v147 row_ror:1 row_mask:0xf bank_mask:0xf
	v_fmac_f32_dpp v160, v152, v148 row_ror:1 row_mask:0xf bank_mask:0xf
	v_fmac_f32_dpp v161, v153, v149 row_ror:1 row_mask:0xf bank_mask:0xf
	v_fmac_f32_dpp v158, v154, v106 row_ror:15 row_mask:0xf bank_mask:0xf
	v_fmac_f32_dpp v159, v155, v107 row_ror:15 row_mask:0xf bank_mask:0xf
	v_fmac_f32_dpp v160, v156, v108 row_ror:15 row_mask:0xf bank_mask:0xf
	v_fmac_f32_dpp v161, v157, v109 row_ror:15 row_mask:0xf bank_mask:0xf
	v_mul_f32_e32 v172, 0xbfb8aa3b, v122
	v_mul_f32_e32 v173, 0xbfb8aa3b, v123
	v_mul_f32_e32 v174, 0xbfb8aa3b, v124
	v_mul_f32_e32 v175, 0xbfb8aa3b, v125
	v_exp_f32_e32 v172, v172
	v_exp_f32_e32 v173, v173
	v_exp_f32_e32 v174, v174
	v_exp_f32_e32 v175, v175
	v_add_f32_e32 v172, 1.0, v172
	v_add_f32_e32 v173, 1.0, v173
	v_add_f32_e32 v174, 1.0, v174
	v_add_f32_e32 v175, 1.0, v175
	v_rcp_f32_e32 v172, v172
	v_rcp_f32_e32 v173, v173
	v_rcp_f32_e32 v174, v174
	v_rcp_f32_e32 v175, v175
	s_mov_b64 s[100:101], 0xb0000
	v_lshl_add_u64 v[234:235], v[232:233], 0, s[100:101]
	v_mul_f32_e32 v172, v122, v172
	v_mul_f32_e32 v173, v123, v173
	v_mul_f32_e32 v174, v124, v174
	v_mul_f32_e32 v175, v125, v175
	v_mul_f32_e32 v172, v172, v158
	v_mul_f32_e32 v173, v173, v159
	v_mul_f32_e32 v174, v174, v160
	v_mul_f32_e32 v175, v175, v161
	v_cvt_pk_bf16_f32 v228, v172, v173
	v_cvt_pk_bf16_f32 v229, v174, v175
	global_store_dwordx2 v[234:235], v[228:229], off offset:8
	v_cndmask_b32_e64 v150, v22, v30, s[40:41]
	v_cndmask_b32_e64 v151, v23, v31, s[40:41]
	v_cndmask_b32_e64 v152, v24, v32, s[40:41]
	v_cndmask_b32_e64 v153, v25, v33, s[40:41]
	v_cndmask_b32_e64 v154, v22, v14, s[42:43]
	v_cndmask_b32_e64 v155, v23, v15, s[42:43]
	v_cndmask_b32_e64 v156, v24, v16, s[42:43]
	v_cndmask_b32_e64 v157, v25, v17, s[42:43]
	v_fma_f32 v122, v22, v118, v102
	v_fma_f32 v123, v23, v119, v103
	v_fma_f32 v124, v24, v120, v104
	v_fma_f32 v125, v25, v121, v105
	v_fmac_f32_dpp v122, v150, v126 row_ror:1 row_mask:0xf bank_mask:0xf
	v_fmac_f32_dpp v123, v151, v127 row_ror:1 row_mask:0xf bank_mask:0xf
	v_fmac_f32_dpp v124, v152, v128 row_ror:1 row_mask:0xf bank_mask:0xf
	v_fmac_f32_dpp v125, v153, v129 row_ror:1 row_mask:0xf bank_mask:0xf
	v_fmac_f32_dpp v122, v154, v110 row_ror:15 row_mask:0xf bank_mask:0xf
	v_fmac_f32_dpp v123, v155, v111 row_ror:15 row_mask:0xf bank_mask:0xf
	v_fmac_f32_dpp v124, v156, v112 row_ror:15 row_mask:0xf bank_mask:0xf
	v_fmac_f32_dpp v125, v157, v113 row_ror:15 row_mask:0xf bank_mask:0xf
	v_cndmask_b32_e64 v150, v18, v26, s[40:41]
	v_cndmask_b32_e64 v151, v19, v27, s[40:41]
	v_cndmask_b32_e64 v152, v20, v28, s[40:41]
	v_cndmask_b32_e64 v153, v21, v29, s[40:41]
	v_cndmask_b32_e64 v154, v18, v10, s[42:43]
	v_cndmask_b32_e64 v155, v19, v11, s[42:43]
	v_cndmask_b32_e64 v156, v20, v12, s[42:43]
	v_cndmask_b32_e64 v157, v21, v13, s[42:43]
	v_fma_f32 v158, v18, v114, v98
	v_fma_f32 v159, v19, v115, v99
	v_fma_f32 v160, v20, v116, v100
	v_fma_f32 v161, v21, v117, v101
	v_fmac_f32_dpp v158, v150, v146 row_ror:1 row_mask:0xf bank_mask:0xf
	v_fmac_f32_dpp v159, v151, v147 row_ror:1 row_mask:0xf bank_mask:0xf
	v_fmac_f32_dpp v160, v152, v148 row_ror:1 row_mask:0xf bank_mask:0xf
	v_fmac_f32_dpp v161, v153, v149 row_ror:1 row_mask:0xf bank_mask:0xf
	v_fmac_f32_dpp v158, v154, v106 row_ror:15 row_mask:0xf bank_mask:0xf
	v_fmac_f32_dpp v159, v155, v107 row_ror:15 row_mask:0xf bank_mask:0xf
	v_fmac_f32_dpp v160, v156, v108 row_ror:15 row_mask:0xf bank_mask:0xf
	v_fmac_f32_dpp v161, v157, v109 row_ror:15 row_mask:0xf bank_mask:0xf
	v_mul_f32_e32 v172, 0xbfb8aa3b, v122
	v_mul_f32_e32 v173, 0xbfb8aa3b, v123
	v_mul_f32_e32 v174, 0xbfb8aa3b, v124
	v_mul_f32_e32 v175, 0xbfb8aa3b, v125
	v_exp_f32_e32 v172, v172
	v_exp_f32_e32 v173, v173
	v_exp_f32_e32 v174, v174
	v_exp_f32_e32 v175, v175
	v_add_f32_e32 v172, 1.0, v172
	v_add_f32_e32 v173, 1.0, v173
	v_add_f32_e32 v174, 1.0, v174
	v_add_f32_e32 v175, 1.0, v175
	v_rcp_f32_e32 v172, v172
	v_rcp_f32_e32 v173, v173
	v_rcp_f32_e32 v174, v174
	v_rcp_f32_e32 v175, v175
	s_mov_b64 s[100:101], 0xc6000
	v_lshl_add_u64 v[234:235], v[232:233], 0, s[100:101]
	v_mul_f32_e32 v172, v122, v172
	v_mul_f32_e32 v173, v123, v173
	v_mul_f32_e32 v174, v124, v174
	v_mul_f32_e32 v175, v125, v175
	v_mul_f32_e32 v172, v172, v158
	v_mul_f32_e32 v173, v173, v159
	v_mul_f32_e32 v174, v174, v160
	v_mul_f32_e32 v175, v175, v161
	v_cvt_pk_bf16_f32 v228, v172, v173
	v_cvt_pk_bf16_f32 v229, v174, v175
	global_store_dwordx2 v[234:235], v[228:229], off offset:8
	v_cndmask_b32_e64 v150, v14, v22, s[40:41]
	v_cndmask_b32_e64 v151, v15, v23, s[40:41]
	v_cndmask_b32_e64 v152, v16, v24, s[40:41]
	v_cndmask_b32_e64 v153, v17, v25, s[40:41]
	v_cndmask_b32_e64 v154, v14, v6, s[42:43]
	v_cndmask_b32_e64 v155, v15, v7, s[42:43]
	v_cndmask_b32_e64 v156, v16, v8, s[42:43]
	v_cndmask_b32_e64 v157, v17, v9, s[42:43]
	v_fma_f32 v122, v14, v118, v102
	v_fma_f32 v123, v15, v119, v103
	v_fma_f32 v124, v16, v120, v104
	v_fma_f32 v125, v17, v121, v105
	v_fmac_f32_dpp v122, v150, v126 row_ror:1 row_mask:0xf bank_mask:0xf
	v_fmac_f32_dpp v123, v151, v127 row_ror:1 row_mask:0xf bank_mask:0xf
	v_fmac_f32_dpp v124, v152, v128 row_ror:1 row_mask:0xf bank_mask:0xf
	v_fmac_f32_dpp v125, v153, v129 row_ror:1 row_mask:0xf bank_mask:0xf
	v_fmac_f32_dpp v122, v154, v110 row_ror:15 row_mask:0xf bank_mask:0xf
	v_fmac_f32_dpp v123, v155, v111 row_ror:15 row_mask:0xf bank_mask:0xf
	v_fmac_f32_dpp v124, v156, v112 row_ror:15 row_mask:0xf bank_mask:0xf
	v_fmac_f32_dpp v125, v157, v113 row_ror:15 row_mask:0xf bank_mask:0xf
	v_cndmask_b32_e64 v150, v10, v18, s[40:41]
	v_cndmask_b32_e64 v151, v11, v19, s[40:41]
	v_cndmask_b32_e64 v152, v12, v20, s[40:41]
	v_cndmask_b32_e64 v153, v13, v21, s[40:41]
	v_cndmask_b32_e64 v154, v10, v2, s[42:43]
	v_cndmask_b32_e64 v155, v11, v3, s[42:43]
	v_cndmask_b32_e64 v156, v12, v4, s[42:43]
	v_cndmask_b32_e64 v157, v13, v5, s[42:43]
	v_fma_f32 v158, v10, v114, v98
	v_fma_f32 v159, v11, v115, v99
	v_fma_f32 v160, v12, v116, v100
	v_fma_f32 v161, v13, v117, v101
	v_fmac_f32_dpp v158, v150, v146 row_ror:1 row_mask:0xf bank_mask:0xf
	v_fmac_f32_dpp v159, v151, v147 row_ror:1 row_mask:0xf bank_mask:0xf
	v_fmac_f32_dpp v160, v152, v148 row_ror:1 row_mask:0xf bank_mask:0xf
	v_fmac_f32_dpp v161, v153, v149 row_ror:1 row_mask:0xf bank_mask:0xf
	v_fmac_f32_dpp v158, v154, v106 row_ror:15 row_mask:0xf bank_mask:0xf
	v_fmac_f32_dpp v159, v155, v107 row_ror:15 row_mask:0xf bank_mask:0xf
	v_fmac_f32_dpp v160, v156, v108 row_ror:15 row_mask:0xf bank_mask:0xf
	v_fmac_f32_dpp v161, v157, v109 row_ror:15 row_mask:0xf bank_mask:0xf
	v_mul_f32_e32 v172, 0xbfb8aa3b, v122
	v_mul_f32_e32 v173, 0xbfb8aa3b, v123
	v_mul_f32_e32 v174, 0xbfb8aa3b, v124
	v_mul_f32_e32 v175, 0xbfb8aa3b, v125
	v_exp_f32_e32 v172, v172
	v_exp_f32_e32 v173, v173
	v_exp_f32_e32 v174, v174
	v_exp_f32_e32 v175, v175
	v_add_f32_e32 v172, 1.0, v172
	v_add_f32_e32 v173, 1.0, v173
	v_add_f32_e32 v174, 1.0, v174
	v_add_f32_e32 v175, 1.0, v175
	v_rcp_f32_e32 v172, v172
	v_rcp_f32_e32 v173, v173
	v_rcp_f32_e32 v174, v174
	v_rcp_f32_e32 v175, v175
	s_mov_b64 s[100:101], 0xdc000
	v_lshl_add_u64 v[234:235], v[232:233], 0, s[100:101]
	v_mul_f32_e32 v172, v122, v172
	v_mul_f32_e32 v173, v123, v173
	v_mul_f32_e32 v174, v124, v174
	v_mul_f32_e32 v175, v125, v175
	v_mul_f32_e32 v172, v172, v158
	v_mul_f32_e32 v173, v173, v159
	v_mul_f32_e32 v174, v174, v160
	v_mul_f32_e32 v175, v175, v161
	v_cvt_pk_bf16_f32 v228, v172, v173
	v_cvt_pk_bf16_f32 v229, v174, v175
	global_store_dwordx2 v[234:235], v[228:229], off offset:8
	s_waitcnt lgkmcnt(0)
	v_cndmask_b32_e64 v150, v6, v14, s[40:41]
	v_cndmask_b32_e64 v151, v7, v15, s[40:41]
	v_cndmask_b32_e64 v152, v8, v16, s[40:41]
	v_cndmask_b32_e64 v153, v9, v17, s[40:41]
	v_cndmask_b32_e64 v154, v6, v138, s[42:43]
	v_cndmask_b32_e64 v155, v7, v139, s[42:43]
	v_cndmask_b32_e64 v156, v8, v140, s[42:43]
	v_cndmask_b32_e64 v157, v9, v141, s[42:43]
	v_fma_f32 v122, v6, v118, v102
	v_fma_f32 v123, v7, v119, v103
	v_fma_f32 v124, v8, v120, v104
	v_fma_f32 v125, v9, v121, v105
	v_fmac_f32_dpp v122, v150, v126 row_ror:1 row_mask:0xf bank_mask:0xf
	v_fmac_f32_dpp v123, v151, v127 row_ror:1 row_mask:0xf bank_mask:0xf
	v_fmac_f32_dpp v124, v152, v128 row_ror:1 row_mask:0xf bank_mask:0xf
	v_fmac_f32_dpp v125, v153, v129 row_ror:1 row_mask:0xf bank_mask:0xf
	v_fmac_f32_dpp v122, v154, v110 row_ror:15 row_mask:0xf bank_mask:0xf
	v_fmac_f32_dpp v123, v155, v111 row_ror:15 row_mask:0xf bank_mask:0xf
	v_fmac_f32_dpp v124, v156, v112 row_ror:15 row_mask:0xf bank_mask:0xf
	v_fmac_f32_dpp v125, v157, v113 row_ror:15 row_mask:0xf bank_mask:0xf
	v_cndmask_b32_e64 v150, v2, v10, s[40:41]
	v_cndmask_b32_e64 v151, v3, v11, s[40:41]
	v_cndmask_b32_e64 v152, v4, v12, s[40:41]
	v_cndmask_b32_e64 v153, v5, v13, s[40:41]
	v_cndmask_b32_e64 v154, v2, v142, s[42:43]
	v_cndmask_b32_e64 v155, v3, v143, s[42:43]
	v_cndmask_b32_e64 v156, v4, v144, s[42:43]
	v_cndmask_b32_e64 v157, v5, v145, s[42:43]
	v_fma_f32 v158, v2, v114, v98
	v_fma_f32 v159, v3, v115, v99
	v_fma_f32 v160, v4, v116, v100
	v_fma_f32 v161, v5, v117, v101
	v_fmac_f32_dpp v158, v150, v146 row_ror:1 row_mask:0xf bank_mask:0xf
	v_fmac_f32_dpp v159, v151, v147 row_ror:1 row_mask:0xf bank_mask:0xf
	v_fmac_f32_dpp v160, v152, v148 row_ror:1 row_mask:0xf bank_mask:0xf
	v_fmac_f32_dpp v161, v153, v149 row_ror:1 row_mask:0xf bank_mask:0xf
	v_fmac_f32_dpp v158, v154, v106 row_ror:15 row_mask:0xf bank_mask:0xf
	v_fmac_f32_dpp v159, v155, v107 row_ror:15 row_mask:0xf bank_mask:0xf
	v_fmac_f32_dpp v160, v156, v108 row_ror:15 row_mask:0xf bank_mask:0xf
	v_fmac_f32_dpp v161, v157, v109 row_ror:15 row_mask:0xf bank_mask:0xf
	v_mul_f32_e32 v172, 0xbfb8aa3b, v122
	v_mul_f32_e32 v173, 0xbfb8aa3b, v123
	v_mul_f32_e32 v174, 0xbfb8aa3b, v124
	v_mul_f32_e32 v175, 0xbfb8aa3b, v125
	v_exp_f32_e32 v172, v172
	v_exp_f32_e32 v173, v173
	v_exp_f32_e32 v174, v174
	v_exp_f32_e32 v175, v175
	v_add_f32_e32 v172, 1.0, v172
	v_add_f32_e32 v173, 1.0, v173
	v_add_f32_e32 v174, 1.0, v174
	v_add_f32_e32 v175, 1.0, v175
	v_rcp_f32_e32 v172, v172
	v_rcp_f32_e32 v173, v173
	v_rcp_f32_e32 v174, v174
	v_rcp_f32_e32 v175, v175
	s_mov_b64 s[100:101], 0xf2000
	v_lshl_add_u64 v[234:235], v[232:233], 0, s[100:101]
	v_mul_f32_e32 v172, v122, v172
	v_mul_f32_e32 v173, v123, v173
	v_mul_f32_e32 v174, v124, v174
	v_mul_f32_e32 v175, v125, v175
	v_mul_f32_e32 v172, v172, v158
	v_mul_f32_e32 v173, v173, v159
	v_mul_f32_e32 v174, v174, v160
	v_mul_f32_e32 v175, v175, v161
	v_cvt_pk_bf16_f32 v228, v172, v173
	v_cvt_pk_bf16_f32 v229, v174, v175
	global_store_dwordx2 v[234:235], v[228:229], off offset:8
	s_and_b64 vcc, exec, s[38:39]
	s_mov_b64 s[0:1], -1
	s_cbranch_vccnz .LBB0_64
	s_andn2_b64 vcc, exec, s[6:7]
	s_cbranch_vccnz .LBB0_63
	s_barrier
	s_branch .LBB0_63
